# combination plus GIN tile hand-written with 16x16x32 MFMA; accumulator init from bias moved before the first-stage wait in the hand-written tiles
# speedup vs baseline: 1.0093x; 1.0006x over previous
.LBB0_115:
	s_lshl_b32 s65, s25, 4
	s_sub_i32 s65, s56, s65
	s_lshl_b32 s65, s65, 8
	s_lshl_b32 vcc_hi, s36, 11
	s_add_u32 s30, s42, vcc_hi
	s_addc_u32 s31, s43, 0
	s_lshl_b32 vcc_hi, s65, 11
	s_add_u32 s52, s44, vcc_hi
	s_addc_u32 s53, s45, 0
	s_waitcnt lgkmcnt(0)
	v_readfirstlane_b32 vcc_hi, v200
	s_lshr_b32 vcc_hi, vcc_hi, 6
	s_lshl_b32 s24, vcc_hi, 11
	s_add_u32 s24, s24, 16
	s_lshl_b32 vcc_hi, vcc_hi, 16
	s_add_u32 s30, s30, vcc_hi
	s_addc_u32 s31, s31, 0
	s_add_u32 s52, s52, vcc_hi
	s_addc_u32 s53, s53, 0
	v_bfe_u32 v173, v200, 4, 2
	v_sub_u32_e32 v173, 0, v173
	v_and_b32_e32 v173, 3, v173
	v_and_b32_e32 v172, 3, v200
	v_xor_b32_e32 v172, v172, v173
	v_bfe_u32 v173, v200, 2, 4
	v_lshlrev_b32_e32 v173, 11, v173
	v_lshl_or_b32 v170, v172, 4, v173
	v_add_u32_e32 v171, 0x8000, v170
	v_bfe_u32 v172, v200, 2, 2
	v_sub_u32_e32 v172, 0, v172
	v_and_b32_e32 v172, 3, v172
	v_bfe_u32 v173, v200, 4, 2
	v_xor_b32_e32 v172, v172, v173
	v_and_b32_e32 v173, 15, v200
	v_bfe_u32 v174, v200, 8, 1
	v_lshl_or_b32 v174, v174, 7, v173
	v_lshlrev_b32_e32 v174, 6, v174
	v_lshl_or_b32 v164, v172, 4, v174
	v_bfe_u32 v174, v200, 6, 2
	v_lshl_or_b32 v174, v174, 6, v173
	v_lshlrev_b32_e32 v174, 6, v174
	v_lshl_or_b32 v165, v172, 4, v174
	v_add_u32_e32 v165, 0x4000, v165
	v_bfe_u32 v172, v200, 6, 2
	v_bfe_u32 v173, v200, 4, 2
	v_lshlrev_b32_e32 v172, 6, v172
	v_lshl_or_b32 v172, v173, 2, v172
	v_add_u32_e32 v172, s65, v172
	v_lshlrev_b32_e32 v172, 2, v172
	global_load_dwordx4 v[132:135], v172, s[54:55]
	global_load_dwordx4 v[136:139], v172, s[54:55] offset:64
	global_load_dwordx4 v[140:143], v172, s[54:55] offset:128
	global_load_dwordx4 v[144:147], v172, s[54:55] offset:192
	s_mov_b32 s37, s24
	s_mov_b32 m0, s37
	s_nop 0
	global_load_lds_dwordx4 v170, s[30:31]
	s_add_u32 m0, s37, 0x400
	s_nop 0
	global_load_lds_dwordx4 v171, s[30:31]
	s_add_u32 m0, s37, 0x4000
	s_nop 0
	global_load_lds_dwordx4 v170, s[52:53]
	s_add_u32 m0, s37, 0x4400
	s_nop 0
	global_load_lds_dwordx4 v171, s[52:53]
	s_add_u32 s30, s30, 64
	s_addc_u32 s31, s31, 0
	s_add_u32 s52, s52, 64
	s_addc_u32 s53, s53, 0
	s_add_u32 s37, s24, 0x8000
	s_mov_b32 m0, s37
	s_nop 0
	global_load_lds_dwordx4 v170, s[30:31]
	s_add_u32 m0, s37, 0x400
	s_nop 0
	global_load_lds_dwordx4 v171, s[30:31]
	s_add_u32 m0, s37, 0x4000
	s_nop 0
	global_load_lds_dwordx4 v170, s[52:53]
	s_add_u32 m0, s37, 0x4400
	s_nop 0
	global_load_lds_dwordx4 v171, s[52:53]
	s_add_u32 s30, s30, 64
	s_addc_u32 s31, s31, 0
	s_add_u32 s52, s52, 64
	s_addc_u32 s53, s53, 0
	s_add_u32 s37, s24, 0x10000
	s_mov_b32 m0, s37
	s_nop 0
	global_load_lds_dwordx4 v170, s[30:31]
	s_add_u32 m0, s37, 0x400
	s_nop 0
	global_load_lds_dwordx4 v171, s[30:31]
	s_add_u32 m0, s37, 0x4000
	s_nop 0
	global_load_lds_dwordx4 v170, s[52:53]
	s_add_u32 m0, s37, 0x4400
	s_nop 0
	global_load_lds_dwordx4 v171, s[52:53]
	s_add_u32 s30, s30, 64
	s_addc_u32 s31, s31, 0
	s_add_u32 s52, s52, 64
	s_addc_u32 s53, s53, 0
	s_add_u32 s37, s24, 0x18000
	s_mov_b32 m0, s37
	s_nop 0
	global_load_lds_dwordx4 v170, s[30:31]
	s_add_u32 m0, s37, 0x400
	s_nop 0
	global_load_lds_dwordx4 v171, s[30:31]
	s_add_u32 m0, s37, 0x4000
	s_nop 0
	global_load_lds_dwordx4 v170, s[52:53]
	s_add_u32 m0, s37, 0x4400
	s_nop 0
	global_load_lds_dwordx4 v171, s[52:53]
	s_add_u32 s30, s30, 64
	s_addc_u32 s31, s31, 0
	s_add_u32 s52, s52, 64
	s_addc_u32 s53, s53, 0
	s_waitcnt vmcnt(16)
	v_mov_b32_e32 v4, v132
	v_mov_b32_e32 v5, v133
	v_mov_b32_e32 v6, v134
	v_mov_b32_e32 v7, v135
	v_mov_b32_e32 v8, v136
	v_mov_b32_e32 v9, v137
	v_mov_b32_e32 v10, v138
	v_mov_b32_e32 v11, v139
	v_mov_b32_e32 v12, v140
	v_mov_b32_e32 v13, v141
	v_mov_b32_e32 v14, v142
	v_mov_b32_e32 v15, v143
	v_mov_b32_e32 v16, v144
	v_mov_b32_e32 v17, v145
	v_mov_b32_e32 v18, v146
	v_mov_b32_e32 v19, v147
	v_mov_b32_e32 v20, v132
	v_mov_b32_e32 v21, v133
	v_mov_b32_e32 v22, v134
	v_mov_b32_e32 v23, v135
	v_mov_b32_e32 v24, v136
	v_mov_b32_e32 v25, v137
	v_mov_b32_e32 v26, v138
	v_mov_b32_e32 v27, v139
	v_mov_b32_e32 v28, v140
	v_mov_b32_e32 v29, v141
	v_mov_b32_e32 v30, v142
	v_mov_b32_e32 v31, v143
	v_mov_b32_e32 v32, v144
	v_mov_b32_e32 v33, v145
	v_mov_b32_e32 v34, v146
	v_mov_b32_e32 v35, v147
	v_mov_b32_e32 v36, v132
	v_mov_b32_e32 v37, v133
	v_mov_b32_e32 v38, v134
	v_mov_b32_e32 v39, v135
	v_mov_b32_e32 v40, v136
	v_mov_b32_e32 v41, v137
	v_mov_b32_e32 v42, v138
	v_mov_b32_e32 v43, v139
	v_mov_b32_e32 v44, v140
	v_mov_b32_e32 v45, v141
	v_mov_b32_e32 v46, v142
	v_mov_b32_e32 v47, v143
	v_mov_b32_e32 v48, v144
	v_mov_b32_e32 v49, v145
	v_mov_b32_e32 v50, v146
	v_mov_b32_e32 v51, v147
	v_mov_b32_e32 v52, v132
	v_mov_b32_e32 v53, v133
	v_mov_b32_e32 v54, v134
	v_mov_b32_e32 v55, v135
	v_mov_b32_e32 v56, v136
	v_mov_b32_e32 v57, v137
	v_mov_b32_e32 v58, v138
	v_mov_b32_e32 v59, v139
	v_mov_b32_e32 v60, v140
	v_mov_b32_e32 v61, v141
	v_mov_b32_e32 v62, v142
	v_mov_b32_e32 v63, v143
	v_mov_b32_e32 v64, v144
	v_mov_b32_e32 v65, v145
	v_mov_b32_e32 v66, v146
	v_mov_b32_e32 v67, v147
	v_mov_b32_e32 v68, v132
	v_mov_b32_e32 v69, v133
	v_mov_b32_e32 v70, v134
	v_mov_b32_e32 v71, v135
	v_mov_b32_e32 v72, v136
	v_mov_b32_e32 v73, v137
	v_mov_b32_e32 v74, v138
	v_mov_b32_e32 v75, v139
	v_mov_b32_e32 v76, v140
	v_mov_b32_e32 v77, v141
	v_mov_b32_e32 v78, v142
	v_mov_b32_e32 v79, v143
	v_mov_b32_e32 v80, v144
	v_mov_b32_e32 v81, v145
	v_mov_b32_e32 v82, v146
	v_mov_b32_e32 v83, v147
	v_mov_b32_e32 v84, v132
	v_mov_b32_e32 v85, v133
	v_mov_b32_e32 v86, v134
	v_mov_b32_e32 v87, v135
	v_mov_b32_e32 v88, v136
	v_mov_b32_e32 v89, v137
	v_mov_b32_e32 v90, v138
	v_mov_b32_e32 v91, v139
	v_mov_b32_e32 v92, v140
	v_mov_b32_e32 v93, v141
	v_mov_b32_e32 v94, v142
	v_mov_b32_e32 v95, v143
	v_mov_b32_e32 v96, v144
	v_mov_b32_e32 v97, v145
	v_mov_b32_e32 v98, v146
	v_mov_b32_e32 v99, v147
	v_mov_b32_e32 v100, v132
	v_mov_b32_e32 v101, v133
	v_mov_b32_e32 v102, v134
	v_mov_b32_e32 v103, v135
	v_mov_b32_e32 v104, v136
	v_mov_b32_e32 v105, v137
	v_mov_b32_e32 v106, v138
	v_mov_b32_e32 v107, v139
	v_mov_b32_e32 v108, v140
	v_mov_b32_e32 v109, v141
	v_mov_b32_e32 v110, v142
	v_mov_b32_e32 v111, v143
	v_mov_b32_e32 v112, v144
	v_mov_b32_e32 v113, v145
	v_mov_b32_e32 v114, v146
	v_mov_b32_e32 v115, v147
	v_mov_b32_e32 v116, v132
	v_mov_b32_e32 v117, v133
	v_mov_b32_e32 v118, v134
	v_mov_b32_e32 v119, v135
	v_mov_b32_e32 v120, v136
	v_mov_b32_e32 v121, v137
	v_mov_b32_e32 v122, v138
	v_mov_b32_e32 v123, v139
	v_mov_b32_e32 v124, v140
	v_mov_b32_e32 v125, v141
	v_mov_b32_e32 v126, v142
	v_mov_b32_e32 v127, v143
	v_mov_b32_e32 v128, v144
	v_mov_b32_e32 v129, v145
	v_mov_b32_e32 v130, v146
	v_mov_b32_e32 v131, v147
	s_waitcnt vmcnt(12)
	s_barrier
	s_mov_b32 s32, 0
	s_mov_b32 s57, 0
	s_nop 1
	v_add_u32_e32 v168, s32, v165
	v_add_u32_e32 v169, s32, v164
	ds_read_b128 v[132:135], v168 offset:16
	ds_read_b128 v[136:139], v168 offset:1040
	ds_read_b128 v[140:143], v168 offset:2064
	ds_read_b128 v[144:147], v168 offset:3088
	ds_read_b128 v[184:187], v169 offset:16
	ds_read_b128 v[188:191], v169 offset:1040
	ds_read_b128 v[192:195], v169 offset:2064
	ds_read_b128 v[196:199], v169 offset:3088
	s_waitcnt lgkmcnt(0)

.LBB0_729:
	s_lshl_b32 s65, s52, 4
	s_sub_i32 s65, s54, s65
	s_lshl_b32 s65, s65, 8
	s_lshl_b32 vcc_hi, s36, 11
	s_add_u32 s30, s42, vcc_hi
	s_addc_u32 s31, s43, 0
	s_lshl_b32 vcc_hi, s65, 11
	s_add_u32 s56, s44, vcc_hi
	s_addc_u32 s57, s45, 0
	s_waitcnt lgkmcnt(0)
	v_readfirstlane_b32 vcc_hi, v200
	s_lshr_b32 vcc_hi, vcc_hi, 6
	s_lshl_b32 s32, vcc_hi, 11
	s_add_u32 s32, s32, 16
	s_lshl_b32 vcc_hi, vcc_hi, 16
	s_add_u32 s30, s30, vcc_hi
	s_addc_u32 s31, s31, 0
	s_add_u32 s56, s56, vcc_hi
	s_addc_u32 s57, s57, 0
	v_bfe_u32 v173, v200, 4, 2
	v_sub_u32_e32 v173, 0, v173
	v_and_b32_e32 v173, 3, v173
	v_and_b32_e32 v172, 3, v200
	v_xor_b32_e32 v172, v172, v173
	v_bfe_u32 v173, v200, 2, 4
	v_lshlrev_b32_e32 v173, 11, v173
	v_lshl_or_b32 v170, v172, 4, v173
	v_add_u32_e32 v171, 0x8000, v170
	v_bfe_u32 v172, v200, 2, 2
	v_sub_u32_e32 v172, 0, v172
	v_and_b32_e32 v172, 3, v172
	v_bfe_u32 v173, v200, 4, 2
	v_xor_b32_e32 v172, v172, v173
	v_and_b32_e32 v173, 15, v200
	v_bfe_u32 v174, v200, 8, 1
	v_lshl_or_b32 v174, v174, 7, v173
	v_lshlrev_b32_e32 v174, 6, v174
	v_lshl_or_b32 v164, v172, 4, v174
	v_bfe_u32 v174, v200, 6, 2
	v_lshl_or_b32 v174, v174, 6, v173
	v_lshlrev_b32_e32 v174, 6, v174
	v_lshl_or_b32 v165, v172, 4, v174
	v_add_u32_e32 v165, 0x4000, v165
	v_bfe_u32 v172, v200, 6, 2
	v_bfe_u32 v173, v200, 4, 2
	v_lshlrev_b32_e32 v172, 6, v172
	v_lshl_or_b32 v172, v173, 2, v172
	v_add_u32_e32 v172, s65, v172
	v_lshlrev_b32_e32 v172, 2, v172
	global_load_dwordx4 v[132:135], v172, s[24:25]
	global_load_dwordx4 v[136:139], v172, s[24:25] offset:64
	global_load_dwordx4 v[140:143], v172, s[24:25] offset:128
	global_load_dwordx4 v[144:147], v172, s[24:25] offset:192
	s_mov_b32 s53, s32
	s_mov_b32 m0, s53
	s_nop 0
	global_load_lds_dwordx4 v170, s[30:31]
	s_add_u32 m0, s53, 0x400
	s_nop 0
	global_load_lds_dwordx4 v171, s[30:31]
	s_add_u32 m0, s53, 0x4000
	s_nop 0
	global_load_lds_dwordx4 v170, s[56:57]
	s_add_u32 m0, s53, 0x4400
	s_nop 0
	global_load_lds_dwordx4 v171, s[56:57]
	s_add_u32 s30, s30, 64
	s_addc_u32 s31, s31, 0
	s_add_u32 s56, s56, 64
	s_addc_u32 s57, s57, 0
	s_add_u32 s53, s32, 0x8000
	s_mov_b32 m0, s53
	s_nop 0
	global_load_lds_dwordx4 v170, s[30:31]
	s_add_u32 m0, s53, 0x400
	s_nop 0
	global_load_lds_dwordx4 v171, s[30:31]
	s_add_u32 m0, s53, 0x4000
	s_nop 0
	global_load_lds_dwordx4 v170, s[56:57]
	s_add_u32 m0, s53, 0x4400
	s_nop 0
	global_load_lds_dwordx4 v171, s[56:57]
	s_add_u32 s30, s30, 64
	s_addc_u32 s31, s31, 0
	s_add_u32 s56, s56, 64
	s_addc_u32 s57, s57, 0
	s_add_u32 s53, s32, 0x10000
	s_mov_b32 m0, s53
	s_nop 0
	global_load_lds_dwordx4 v170, s[30:31]
	s_add_u32 m0, s53, 0x400
	s_nop 0
	global_load_lds_dwordx4 v171, s[30:31]
	s_add_u32 m0, s53, 0x4000
	s_nop 0
	global_load_lds_dwordx4 v170, s[56:57]
	s_add_u32 m0, s53, 0x4400
	s_nop 0
	global_load_lds_dwordx4 v171, s[56:57]
	s_add_u32 s30, s30, 64
	s_addc_u32 s31, s31, 0
	s_add_u32 s56, s56, 64
	s_addc_u32 s57, s57, 0
	s_add_u32 s53, s32, 0x18000
	s_mov_b32 m0, s53
	s_nop 0
	global_load_lds_dwordx4 v170, s[30:31]
	s_add_u32 m0, s53, 0x400
	s_nop 0
	global_load_lds_dwordx4 v171, s[30:31]
	s_add_u32 m0, s53, 0x4000
	s_nop 0
	global_load_lds_dwordx4 v170, s[56:57]
	s_add_u32 m0, s53, 0x4400
	s_nop 0
	global_load_lds_dwordx4 v171, s[56:57]
	s_add_u32 s30, s30, 64
	s_addc_u32 s31, s31, 0
	s_add_u32 s56, s56, 64
	s_addc_u32 s57, s57, 0
	s_waitcnt vmcnt(16)
	v_mov_b32_e32 v4, v132
	v_mov_b32_e32 v5, v133
	v_mov_b32_e32 v6, v134
	v_mov_b32_e32 v7, v135
	v_mov_b32_e32 v8, v136
	v_mov_b32_e32 v9, v137
	v_mov_b32_e32 v10, v138
	v_mov_b32_e32 v11, v139
	v_mov_b32_e32 v12, v140
	v_mov_b32_e32 v13, v141
	v_mov_b32_e32 v14, v142
	v_mov_b32_e32 v15, v143
	v_mov_b32_e32 v16, v144
	v_mov_b32_e32 v17, v145
	v_mov_b32_e32 v18, v146
	v_mov_b32_e32 v19, v147
	v_mov_b32_e32 v20, v132
	v_mov_b32_e32 v21, v133
	v_mov_b32_e32 v22, v134
	v_mov_b32_e32 v23, v135
	v_mov_b32_e32 v24, v136
	v_mov_b32_e32 v25, v137
	v_mov_b32_e32 v26, v138
	v_mov_b32_e32 v27, v139
	v_mov_b32_e32 v28, v140
	v_mov_b32_e32 v29, v141
	v_mov_b32_e32 v30, v142
	v_mov_b32_e32 v31, v143
	v_mov_b32_e32 v32, v144
	v_mov_b32_e32 v33, v145
	v_mov_b32_e32 v34, v146
	v_mov_b32_e32 v35, v147
	v_mov_b32_e32 v36, v132
	v_mov_b32_e32 v37, v133
	v_mov_b32_e32 v38, v134
	v_mov_b32_e32 v39, v135
	v_mov_b32_e32 v40, v136
	v_mov_b32_e32 v41, v137
	v_mov_b32_e32 v42, v138
	v_mov_b32_e32 v43, v139
	v_mov_b32_e32 v44, v140
	v_mov_b32_e32 v45, v141
	v_mov_b32_e32 v46, v142
	v_mov_b32_e32 v47, v143
	v_mov_b32_e32 v48, v144
	v_mov_b32_e32 v49, v145
	v_mov_b32_e32 v50, v146
	v_mov_b32_e32 v51, v147
	v_mov_b32_e32 v52, v132
	v_mov_b32_e32 v53, v133
	v_mov_b32_e32 v54, v134
	v_mov_b32_e32 v55, v135
	v_mov_b32_e32 v56, v136
	v_mov_b32_e32 v57, v137
	v_mov_b32_e32 v58, v138
	v_mov_b32_e32 v59, v139
	v_mov_b32_e32 v60, v140
	v_mov_b32_e32 v61, v141
	v_mov_b32_e32 v62, v142
	v_mov_b32_e32 v63, v143
	v_mov_b32_e32 v64, v144
	v_mov_b32_e32 v65, v145
	v_mov_b32_e32 v66, v146
	v_mov_b32_e32 v67, v147
	v_mov_b32_e32 v68, v132
	v_mov_b32_e32 v69, v133
	v_mov_b32_e32 v70, v134
	v_mov_b32_e32 v71, v135
	v_mov_b32_e32 v72, v136
	v_mov_b32_e32 v73, v137
	v_mov_b32_e32 v74, v138
	v_mov_b32_e32 v75, v139
	v_mov_b32_e32 v76, v140
	v_mov_b32_e32 v77, v141
	v_mov_b32_e32 v78, v142
	v_mov_b32_e32 v79, v143
	v_mov_b32_e32 v80, v144
	v_mov_b32_e32 v81, v145
	v_mov_b32_e32 v82, v146
	v_mov_b32_e32 v83, v147
	v_mov_b32_e32 v84, v132
	v_mov_b32_e32 v85, v133
	v_mov_b32_e32 v86, v134
	v_mov_b32_e32 v87, v135
	v_mov_b32_e32 v88, v136
	v_mov_b32_e32 v89, v137
	v_mov_b32_e32 v90, v138
	v_mov_b32_e32 v91, v139
	v_mov_b32_e32 v92, v140
	v_mov_b32_e32 v93, v141
	v_mov_b32_e32 v94, v142
	v_mov_b32_e32 v95, v143
	v_mov_b32_e32 v96, v144
	v_mov_b32_e32 v97, v145
	v_mov_b32_e32 v98, v146
	v_mov_b32_e32 v99, v147
	v_mov_b32_e32 v100, v132
	v_mov_b32_e32 v101, v133
	v_mov_b32_e32 v102, v134
	v_mov_b32_e32 v103, v135
	v_mov_b32_e32 v104, v136
	v_mov_b32_e32 v105, v137
	v_mov_b32_e32 v106, v138
	v_mov_b32_e32 v107, v139
	v_mov_b32_e32 v108, v140
	v_mov_b32_e32 v109, v141
	v_mov_b32_e32 v110, v142
	v_mov_b32_e32 v111, v143
	v_mov_b32_e32 v112, v144
	v_mov_b32_e32 v113, v145
	v_mov_b32_e32 v114, v146
	v_mov_b32_e32 v115, v147
	v_mov_b32_e32 v116, v132
	v_mov_b32_e32 v117, v133
	v_mov_b32_e32 v118, v134
	v_mov_b32_e32 v119, v135
	v_mov_b32_e32 v120, v136
	v_mov_b32_e32 v121, v137
	v_mov_b32_e32 v122, v138
	v_mov_b32_e32 v123, v139
	v_mov_b32_e32 v124, v140
	v_mov_b32_e32 v125, v141
	v_mov_b32_e32 v126, v142
	v_mov_b32_e32 v127, v143
	v_mov_b32_e32 v128, v144
	v_mov_b32_e32 v129, v145
	v_mov_b32_e32 v130, v146
	v_mov_b32_e32 v131, v147
	s_waitcnt vmcnt(12)
	s_barrier
	s_mov_b32 s37, 0
	s_mov_b32 s55, 0
	s_nop 1
	v_add_u32_e32 v168, s37, v165
	v_add_u32_e32 v169, s37, v164
	ds_read_b128 v[132:135], v168 offset:16
	ds_read_b128 v[136:139], v168 offset:1040
	ds_read_b128 v[140:143], v168 offset:2064
	ds_read_b128 v[144:147], v168 offset:3088
	ds_read_b128 v[184:187], v169 offset:16
	ds_read_b128 v[188:191], v169 offset:1040
	ds_read_b128 v[192:195], v169 offset:2064
	ds_read_b128 v[196:199], v169 offset:3088
	s_waitcnt lgkmcnt(0)

.LBB0_1121:
	s_mul_hi_i32 s50, s46, 0x2aaaaaab
	s_lshr_b32 s51, s50, 31
	s_add_i32 s50, s50, s51
	s_lshl_b32 s51, s50, 3
	s_or_b32 s51, s51, s83
	s_and_b64 vcc, s[74:75], exec
	s_cselect_b32 s52, s51, s50
	s_mul_i32 s51, s50, 6
	s_sub_i32 s51, s46, s51
	s_lshl_b32 s51, s51, 8
	s_lshl_b32 s52, s52, 8
	s_load_dwordx2 s[44:45], s[22:23], 0x90
	s_lshl_b32 s50, s52, 11
	s_add_u32 s36, s26, s50
	s_addc_u32 s37, s27, 0
	s_lshl_b32 s50, s51, 11
	s_add_u32 s42, s24, s50
	s_addc_u32 s43, s25, 0
	s_waitcnt lgkmcnt(0)
	v_readfirstlane_b32 s50, v200
	s_lshr_b32 s50, s50, 6
	s_lshl_b32 s32, s50, 11
	s_add_u32 s32, s32, 16
	s_lshl_b32 s50, s50, 16
	s_add_u32 s36, s36, s50
	s_addc_u32 s37, s37, 0
	s_add_u32 s42, s42, s50
	s_addc_u32 s43, s43, 0
	v_bfe_u32 v173, v200, 4, 2
	v_sub_u32_e32 v173, 0, v173
	v_and_b32_e32 v173, 3, v173
	v_and_b32_e32 v172, 3, v200
	v_xor_b32_e32 v172, v172, v173
	v_bfe_u32 v173, v200, 2, 4
	v_lshlrev_b32_e32 v173, 11, v173
	v_lshl_or_b32 v170, v172, 4, v173
	v_add_u32_e32 v171, 0x8000, v170
	v_bfe_u32 v172, v200, 2, 2
	v_sub_u32_e32 v172, 0, v172
	v_and_b32_e32 v172, 3, v172
	v_bfe_u32 v173, v200, 4, 2
	v_xor_b32_e32 v172, v172, v173
	v_and_b32_e32 v173, 15, v200
	v_bfe_u32 v174, v200, 8, 1
	v_lshl_or_b32 v174, v174, 7, v173
	v_lshlrev_b32_e32 v174, 6, v174
	v_lshl_or_b32 v164, v172, 4, v174
	v_bfe_u32 v174, v200, 6, 2
	v_lshl_or_b32 v174, v174, 6, v173
	v_lshlrev_b32_e32 v174, 6, v174
	v_lshl_or_b32 v165, v172, 4, v174
	v_add_u32_e32 v165, 0x4000, v165
	v_bfe_u32 v172, v200, 6, 2
	v_bfe_u32 v173, v200, 4, 2
	v_lshlrev_b32_e32 v172, 6, v172
	v_lshl_or_b32 v172, v173, 2, v172
	v_add_u32_e32 v172, s51, v172
	v_lshlrev_b32_e32 v172, 2, v172
	global_load_dwordx4 v[132:135], v172, s[44:45]
	global_load_dwordx4 v[136:139], v172, s[44:45] offset:64
	global_load_dwordx4 v[140:143], v172, s[44:45] offset:128
	global_load_dwordx4 v[144:147], v172, s[44:45] offset:192
	s_mov_b32 s48, s32
	s_mov_b32 m0, s48
	s_nop 0
	global_load_lds_dwordx4 v170, s[36:37]
	s_add_u32 m0, s48, 0x400
	s_nop 0
	global_load_lds_dwordx4 v171, s[36:37]
	s_add_u32 m0, s48, 0x4000
	s_nop 0
	global_load_lds_dwordx4 v170, s[42:43]
	s_add_u32 m0, s48, 0x4400
	s_nop 0
	global_load_lds_dwordx4 v171, s[42:43]
	s_add_u32 s36, s36, 64
	s_addc_u32 s37, s37, 0
	s_add_u32 s42, s42, 64
	s_addc_u32 s43, s43, 0
	s_add_u32 s48, s32, 0x8000
	s_mov_b32 m0, s48
	s_nop 0
	global_load_lds_dwordx4 v170, s[36:37]
	s_add_u32 m0, s48, 0x400
	s_nop 0
	global_load_lds_dwordx4 v171, s[36:37]
	s_add_u32 m0, s48, 0x4000
	s_nop 0
	global_load_lds_dwordx4 v170, s[42:43]
	s_add_u32 m0, s48, 0x4400
	s_nop 0
	global_load_lds_dwordx4 v171, s[42:43]
	s_add_u32 s36, s36, 64
	s_addc_u32 s37, s37, 0
	s_add_u32 s42, s42, 64
	s_addc_u32 s43, s43, 0
	s_add_u32 s48, s32, 0x10000
	s_mov_b32 m0, s48
	s_nop 0
	global_load_lds_dwordx4 v170, s[36:37]
	s_add_u32 m0, s48, 0x400
	s_nop 0
	global_load_lds_dwordx4 v171, s[36:37]
	s_add_u32 m0, s48, 0x4000
	s_nop 0
	global_load_lds_dwordx4 v170, s[42:43]
	s_add_u32 m0, s48, 0x4400
	s_nop 0
	global_load_lds_dwordx4 v171, s[42:43]
	s_add_u32 s36, s36, 64
	s_addc_u32 s37, s37, 0
	s_add_u32 s42, s42, 64
	s_addc_u32 s43, s43, 0
	s_add_u32 s48, s32, 0x18000
	s_mov_b32 m0, s48
	s_nop 0
	global_load_lds_dwordx4 v170, s[36:37]
	s_add_u32 m0, s48, 0x400
	s_nop 0
	global_load_lds_dwordx4 v171, s[36:37]
	s_add_u32 m0, s48, 0x4000
	s_nop 0
	global_load_lds_dwordx4 v170, s[42:43]
	s_add_u32 m0, s48, 0x4400
	s_nop 0
	global_load_lds_dwordx4 v171, s[42:43]
	s_add_u32 s36, s36, 64
	s_addc_u32 s37, s37, 0
	s_add_u32 s42, s42, 64
	s_addc_u32 s43, s43, 0
	s_waitcnt vmcnt(16)
	v_mov_b32_e32 v4, v132
	v_mov_b32_e32 v5, v133
	v_mov_b32_e32 v6, v134
	v_mov_b32_e32 v7, v135
	v_mov_b32_e32 v8, v136
	v_mov_b32_e32 v9, v137
	v_mov_b32_e32 v10, v138
	v_mov_b32_e32 v11, v139
	v_mov_b32_e32 v12, v140
	v_mov_b32_e32 v13, v141
	v_mov_b32_e32 v14, v142
	v_mov_b32_e32 v15, v143
	v_mov_b32_e32 v16, v144
	v_mov_b32_e32 v17, v145
	v_mov_b32_e32 v18, v146
	v_mov_b32_e32 v19, v147
	v_mov_b32_e32 v20, v132
	v_mov_b32_e32 v21, v133
	v_mov_b32_e32 v22, v134
	v_mov_b32_e32 v23, v135
	v_mov_b32_e32 v24, v136
	v_mov_b32_e32 v25, v137
	v_mov_b32_e32 v26, v138
	v_mov_b32_e32 v27, v139
	v_mov_b32_e32 v28, v140
	v_mov_b32_e32 v29, v141
	v_mov_b32_e32 v30, v142
	v_mov_b32_e32 v31, v143
	v_mov_b32_e32 v32, v144
	v_mov_b32_e32 v33, v145
	v_mov_b32_e32 v34, v146
	v_mov_b32_e32 v35, v147
	v_mov_b32_e32 v36, v132
	v_mov_b32_e32 v37, v133
	v_mov_b32_e32 v38, v134
	v_mov_b32_e32 v39, v135
	v_mov_b32_e32 v40, v136
	v_mov_b32_e32 v41, v137
	v_mov_b32_e32 v42, v138
	v_mov_b32_e32 v43, v139
	v_mov_b32_e32 v44, v140
	v_mov_b32_e32 v45, v141
	v_mov_b32_e32 v46, v142
	v_mov_b32_e32 v47, v143
	v_mov_b32_e32 v48, v144
	v_mov_b32_e32 v49, v145
	v_mov_b32_e32 v50, v146
	v_mov_b32_e32 v51, v147
	v_mov_b32_e32 v52, v132
	v_mov_b32_e32 v53, v133
	v_mov_b32_e32 v54, v134
	v_mov_b32_e32 v55, v135
	v_mov_b32_e32 v56, v136
	v_mov_b32_e32 v57, v137
	v_mov_b32_e32 v58, v138
	v_mov_b32_e32 v59, v139
	v_mov_b32_e32 v60, v140
	v_mov_b32_e32 v61, v141
	v_mov_b32_e32 v62, v142
	v_mov_b32_e32 v63, v143
	v_mov_b32_e32 v64, v144
	v_mov_b32_e32 v65, v145
	v_mov_b32_e32 v66, v146
	v_mov_b32_e32 v67, v147
	v_mov_b32_e32 v68, v132
	v_mov_b32_e32 v69, v133
	v_mov_b32_e32 v70, v134
	v_mov_b32_e32 v71, v135
	v_mov_b32_e32 v72, v136
	v_mov_b32_e32 v73, v137
	v_mov_b32_e32 v74, v138
	v_mov_b32_e32 v75, v139
	v_mov_b32_e32 v76, v140
	v_mov_b32_e32 v77, v141
	v_mov_b32_e32 v78, v142
	v_mov_b32_e32 v79, v143
	v_mov_b32_e32 v80, v144
	v_mov_b32_e32 v81, v145
	v_mov_b32_e32 v82, v146
	v_mov_b32_e32 v83, v147
	v_mov_b32_e32 v84, v132
	v_mov_b32_e32 v85, v133
	v_mov_b32_e32 v86, v134
	v_mov_b32_e32 v87, v135
	v_mov_b32_e32 v88, v136
	v_mov_b32_e32 v89, v137
	v_mov_b32_e32 v90, v138
	v_mov_b32_e32 v91, v139
	v_mov_b32_e32 v92, v140
	v_mov_b32_e32 v93, v141
	v_mov_b32_e32 v94, v142
	v_mov_b32_e32 v95, v143
	v_mov_b32_e32 v96, v144
	v_mov_b32_e32 v97, v145
	v_mov_b32_e32 v98, v146
	v_mov_b32_e32 v99, v147
	v_mov_b32_e32 v100, v132
	v_mov_b32_e32 v101, v133
	v_mov_b32_e32 v102, v134
	v_mov_b32_e32 v103, v135
	v_mov_b32_e32 v104, v136
	v_mov_b32_e32 v105, v137
	v_mov_b32_e32 v106, v138
	v_mov_b32_e32 v107, v139
	v_mov_b32_e32 v108, v140
	v_mov_b32_e32 v109, v141
	v_mov_b32_e32 v110, v142
	v_mov_b32_e32 v111, v143
	v_mov_b32_e32 v112, v144
	v_mov_b32_e32 v113, v145
	v_mov_b32_e32 v114, v146
	v_mov_b32_e32 v115, v147
	v_mov_b32_e32 v116, v132
	v_mov_b32_e32 v117, v133
	v_mov_b32_e32 v118, v134
	v_mov_b32_e32 v119, v135
	v_mov_b32_e32 v120, v136
	v_mov_b32_e32 v121, v137
	v_mov_b32_e32 v122, v138
	v_mov_b32_e32 v123, v139
	v_mov_b32_e32 v124, v140
	v_mov_b32_e32 v125, v141
	v_mov_b32_e32 v126, v142
	v_mov_b32_e32 v127, v143
	v_mov_b32_e32 v128, v144
	v_mov_b32_e32 v129, v145
	v_mov_b32_e32 v130, v146
	v_mov_b32_e32 v131, v147
	s_waitcnt vmcnt(12)
	s_barrier
	s_mov_b32 s47, 0
	s_mov_b32 s49, 0
	s_nop 1
	v_add_u32_e32 v168, s47, v165
	v_add_u32_e32 v169, s47, v164
	ds_read_b128 v[132:135], v168 offset:16
	ds_read_b128 v[136:139], v168 offset:1040
	ds_read_b128 v[140:143], v168 offset:2064
	ds_read_b128 v[144:147], v168 offset:3088
	ds_read_b128 v[184:187], v169 offset:16
	ds_read_b128 v[188:191], v169 offset:1040
	ds_read_b128 v[192:195], v169 offset:2064
	ds_read_b128 v[196:199], v169 offset:3088
	s_waitcnt lgkmcnt(0)
.Lt_gin:
	v_add_u32_e32 v169, s47, v164
	v_mfma_f32_16x16x32_f16 v[4:7], v[132:135], v[184:187], v[4:7]
	ds_read_b128 v[238:241], v169 offset:4112
	v_mfma_f32_16x16x32_f16 v[8:11], v[136:139], v[184:187], v[8:11]
	ds_read_b128 v[242:245], v169 offset:5136
	v_mfma_f32_16x16x32_f16 v[12:15], v[140:143], v[184:187], v[12:15]
	ds_read_b128 v[246:249], v169 offset:6160
	v_mfma_f32_16x16x32_f16 v[16:19], v[144:147], v[184:187], v[16:19]
	ds_read_b128 v[250:253], v169 offset:7184
	v_mfma_f32_16x16x32_f16 v[20:23], v[132:135], v[188:191], v[20:23]
	v_mfma_f32_16x16x32_f16 v[24:27], v[136:139], v[188:191], v[24:27]
	v_mfma_f32_16x16x32_f16 v[28:31], v[140:143], v[188:191], v[28:31]
	v_mfma_f32_16x16x32_f16 v[32:35], v[144:147], v[188:191], v[32:35]
	v_mfma_f32_16x16x32_f16 v[36:39], v[132:135], v[192:195], v[36:39]
	v_mfma_f32_16x16x32_f16 v[40:43], v[136:139], v[192:195], v[40:43]
	v_mfma_f32_16x16x32_f16 v[44:47], v[140:143], v[192:195], v[44:47]
	v_mfma_f32_16x16x32_f16 v[48:51], v[144:147], v[192:195], v[48:51]
	v_mfma_f32_16x16x32_f16 v[52:55], v[132:135], v[196:199], v[52:55]
	v_mfma_f32_16x16x32_f16 v[56:59], v[136:139], v[196:199], v[56:59]
	v_mfma_f32_16x16x32_f16 v[60:63], v[140:143], v[196:199], v[60:63]
	v_mfma_f32_16x16x32_f16 v[64:67], v[144:147], v[196:199], v[64:67]
	s_waitcnt vmcnt(8) lgkmcnt(0)
	s_barrier
	s_add_i32 s48, s47, 0x8000
	s_cmp_lg_u32 s47, 0x18000
	s_cselect_b32 s48, s48, 0
	v_add_u32_e32 v168, s48, v165
	v_add_u32_e32 v169, s48, v164
	s_add_u32 vcc_lo, s32, s47
	v_mfma_f32_16x16x32_f16 v[68:71], v[132:135], v[238:241], v[68:71]
	ds_read_b128 v[148:151], v168 offset:16
	ds_read_b128 v[184:187], v169 offset:16
	v_mfma_f32_16x16x32_f16 v[72:75], v[136:139], v[238:241], v[72:75]
	ds_read_b128 v[152:155], v168 offset:1040
	ds_read_b128 v[188:191], v169 offset:1040
	v_mfma_f32_16x16x32_f16 v[76:79], v[140:143], v[238:241], v[76:79]
	ds_read_b128 v[156:159], v168 offset:2064
	ds_read_b128 v[192:195], v169 offset:2064
	v_mfma_f32_16x16x32_f16 v[80:83], v[144:147], v[238:241], v[80:83]
	ds_read_b128 v[160:163], v168 offset:3088
	ds_read_b128 v[196:199], v169 offset:3088
	v_mfma_f32_16x16x32_f16 v[84:87], v[132:135], v[242:245], v[84:87]
	v_mfma_f32_16x16x32_f16 v[88:91], v[136:139], v[242:245], v[88:91]
	v_mfma_f32_16x16x32_f16 v[92:95], v[140:143], v[242:245], v[92:95]
	v_mfma_f32_16x16x32_f16 v[96:99], v[144:147], v[242:245], v[96:99]
	v_mfma_f32_16x16x32_f16 v[100:103], v[132:135], v[246:249], v[100:103]
	s_mov_b32 m0, vcc_lo
	s_nop 0
	global_load_lds_dwordx4 v170, s[36:37]
	v_mfma_f32_16x16x32_f16 v[104:107], v[136:139], v[246:249], v[104:107]
	s_add_u32 m0, vcc_lo, 0x400
	s_nop 0
	global_load_lds_dwordx4 v171, s[36:37]
	v_mfma_f32_16x16x32_f16 v[108:111], v[140:143], v[246:249], v[108:111]
	s_add_u32 m0, vcc_lo, 0x4000
	s_nop 0
	global_load_lds_dwordx4 v170, s[42:43]
	v_mfma_f32_16x16x32_f16 v[112:115], v[144:147], v[246:249], v[112:115]
	s_add_u32 m0, vcc_lo, 0x4400
	s_nop 0
	global_load_lds_dwordx4 v171, s[42:43]
	v_mfma_f32_16x16x32_f16 v[116:119], v[132:135], v[250:253], v[116:119]
	v_mfma_f32_16x16x32_f16 v[120:123], v[136:139], v[250:253], v[120:123]
	v_mfma_f32_16x16x32_f16 v[124:127], v[140:143], v[250:253], v[124:127]
	v_mfma_f32_16x16x32_f16 v[128:131], v[144:147], v[250:253], v[128:131]
	s_waitcnt lgkmcnt(0)
	s_mov_b32 s47, s48
	s_add_u32 s36, s36, 64
	s_addc_u32 s37, s37, 0
	s_add_u32 s42, s42, 64
	s_addc_u32 s43, s43, 0
	v_add_u32_e32 v169, s47, v164
	v_mfma_f32_16x16x32_f16 v[4:7], v[148:151], v[184:187], v[4:7]
	ds_read_b128 v[238:241], v169 offset:4112
	v_mfma_f32_16x16x32_f16 v[8:11], v[152:155], v[184:187], v[8:11]
	ds_read_b128 v[242:245], v169 offset:5136
	v_mfma_f32_16x16x32_f16 v[12:15], v[156:159], v[184:187], v[12:15]
	ds_read_b128 v[246:249], v169 offset:6160
	v_mfma_f32_16x16x32_f16 v[16:19], v[160:163], v[184:187], v[16:19]
	ds_read_b128 v[250:253], v169 offset:7184
	v_mfma_f32_16x16x32_f16 v[20:23], v[148:151], v[188:191], v[20:23]
	v_mfma_f32_16x16x32_f16 v[24:27], v[152:155], v[188:191], v[24:27]
	v_mfma_f32_16x16x32_f16 v[28:31], v[156:159], v[188:191], v[28:31]
	v_mfma_f32_16x16x32_f16 v[32:35], v[160:163], v[188:191], v[32:35]
	v_mfma_f32_16x16x32_f16 v[36:39], v[148:151], v[192:195], v[36:39]
	v_mfma_f32_16x16x32_f16 v[40:43], v[152:155], v[192:195], v[40:43]
	v_mfma_f32_16x16x32_f16 v[44:47], v[156:159], v[192:195], v[44:47]
	v_mfma_f32_16x16x32_f16 v[48:51], v[160:163], v[192:195], v[48:51]
	v_mfma_f32_16x16x32_f16 v[52:55], v[148:151], v[196:199], v[52:55]
	v_mfma_f32_16x16x32_f16 v[56:59], v[152:155], v[196:199], v[56:59]
	v_mfma_f32_16x16x32_f16 v[60:63], v[156:159], v[196:199], v[60:63]
	v_mfma_f32_16x16x32_f16 v[64:67], v[160:163], v[196:199], v[64:67]
	s_waitcnt vmcnt(8) lgkmcnt(0)
	s_barrier
	s_add_i32 s48, s47, 0x8000
	s_cmp_lg_u32 s47, 0x18000
	s_cselect_b32 s48, s48, 0
	v_add_u32_e32 v168, s48, v165
	v_add_u32_e32 v169, s48, v164
	s_add_u32 vcc_lo, s32, s47
	v_mfma_f32_16x16x32_f16 v[68:71], v[148:151], v[238:241], v[68:71]
	ds_read_b128 v[132:135], v168 offset:16
	ds_read_b128 v[184:187], v169 offset:16
	v_mfma_f32_16x16x32_f16 v[72:75], v[152:155], v[238:241], v[72:75]
	ds_read_b128 v[136:139], v168 offset:1040
	ds_read_b128 v[188:191], v169 offset:1040
	v_mfma_f32_16x16x32_f16 v[76:79], v[156:159], v[238:241], v[76:79]
	ds_read_b128 v[140:143], v168 offset:2064
	ds_read_b128 v[192:195], v169 offset:2064
	v_mfma_f32_16x16x32_f16 v[80:83], v[160:163], v[238:241], v[80:83]
	ds_read_b128 v[144:147], v168 offset:3088
	ds_read_b128 v[196:199], v169 offset:3088
	v_mfma_f32_16x16x32_f16 v[84:87], v[148:151], v[242:245], v[84:87]
	v_mfma_f32_16x16x32_f16 v[88:91], v[152:155], v[242:245], v[88:91]
	v_mfma_f32_16x16x32_f16 v[92:95], v[156:159], v[242:245], v[92:95]
	v_mfma_f32_16x16x32_f16 v[96:99], v[160:163], v[242:245], v[96:99]
	v_mfma_f32_16x16x32_f16 v[100:103], v[148:151], v[246:249], v[100:103]
	s_mov_b32 m0, vcc_lo
	s_nop 0
	global_load_lds_dwordx4 v170, s[36:37]
	v_mfma_f32_16x16x32_f16 v[104:107], v[152:155], v[246:249], v[104:107]
	s_add_u32 m0, vcc_lo, 0x400
	s_nop 0
	global_load_lds_dwordx4 v171, s[36:37]
	v_mfma_f32_16x16x32_f16 v[108:111], v[156:159], v[246:249], v[108:111]
	s_add_u32 m0, vcc_lo, 0x4000
	s_nop 0
	global_load_lds_dwordx4 v170, s[42:43]
	v_mfma_f32_16x16x32_f16 v[112:115], v[160:163], v[246:249], v[112:115]
	s_add_u32 m0, vcc_lo, 0x4400
	s_nop 0
	global_load_lds_dwordx4 v171, s[42:43]
	v_mfma_f32_16x16x32_f16 v[116:119], v[148:151], v[250:253], v[116:119]
	v_mfma_f32_16x16x32_f16 v[120:123], v[152:155], v[250:253], v[120:123]
	v_mfma_f32_16x16x32_f16 v[124:127], v[156:159], v[250:253], v[124:127]
	v_mfma_f32_16x16x32_f16 v[128:131], v[160:163], v[250:253], v[128:131]
	s_waitcnt lgkmcnt(0)
	s_mov_b32 s47, s48
	s_add_u32 s36, s36, 64
	s_addc_u32 s37, s37, 0
	s_add_u32 s42, s42, 64
	s_addc_u32 s43, s43, 0
	s_add_i32 s49, s49, 2
	s_cmp_lt_u32 s49, 28
	s_cbranch_scc1 .Lt_gin
	v_add_u32_e32 v169, s47, v164
	v_mfma_f32_16x16x32_f16 v[4:7], v[132:135], v[184:187], v[4:7]
	ds_read_b128 v[238:241], v169 offset:4112
	v_mfma_f32_16x16x32_f16 v[8:11], v[136:139], v[184:187], v[8:11]
	ds_read_b128 v[242:245], v169 offset:5136
	v_mfma_f32_16x16x32_f16 v[12:15], v[140:143], v[184:187], v[12:15]
	ds_read_b128 v[246:249], v169 offset:6160
	v_mfma_f32_16x16x32_f16 v[16:19], v[144:147], v[184:187], v[16:19]
	ds_read_b128 v[250:253], v169 offset:7184
	v_mfma_f32_16x16x32_f16 v[20:23], v[132:135], v[188:191], v[20:23]
	v_mfma_f32_16x16x32_f16 v[24:27], v[136:139], v[188:191], v[24:27]
	v_mfma_f32_16x16x32_f16 v[28:31], v[140:143], v[188:191], v[28:31]
	v_mfma_f32_16x16x32_f16 v[32:35], v[144:147], v[188:191], v[32:35]
	v_mfma_f32_16x16x32_f16 v[36:39], v[132:135], v[192:195], v[36:39]
	v_mfma_f32_16x16x32_f16 v[40:43], v[136:139], v[192:195], v[40:43]
	v_mfma_f32_16x16x32_f16 v[44:47], v[140:143], v[192:195], v[44:47]
	v_mfma_f32_16x16x32_f16 v[48:51], v[144:147], v[192:195], v[48:51]
	v_mfma_f32_16x16x32_f16 v[52:55], v[132:135], v[196:199], v[52:55]
	v_mfma_f32_16x16x32_f16 v[56:59], v[136:139], v[196:199], v[56:59]
	v_mfma_f32_16x16x32_f16 v[60:63], v[140:143], v[196:199], v[60:63]
	v_mfma_f32_16x16x32_f16 v[64:67], v[144:147], v[196:199], v[64:67]
	s_waitcnt vmcnt(8) lgkmcnt(0)
	s_barrier
	s_add_i32 s48, s47, 0x8000
	s_cmp_lg_u32 s47, 0x18000
	s_cselect_b32 s48, s48, 0
	v_add_u32_e32 v168, s48, v165
	v_add_u32_e32 v169, s48, v164
	v_mfma_f32_16x16x32_f16 v[68:71], v[132:135], v[238:241], v[68:71]
	ds_read_b128 v[148:151], v168 offset:16
	ds_read_b128 v[184:187], v169 offset:16
	v_mfma_f32_16x16x32_f16 v[72:75], v[136:139], v[238:241], v[72:75]
	ds_read_b128 v[152:155], v168 offset:1040
	ds_read_b128 v[188:191], v169 offset:1040
	v_mfma_f32_16x16x32_f16 v[76:79], v[140:143], v[238:241], v[76:79]
	ds_read_b128 v[156:159], v168 offset:2064
	ds_read_b128 v[192:195], v169 offset:2064
	v_mfma_f32_16x16x32_f16 v[80:83], v[144:147], v[238:241], v[80:83]
	ds_read_b128 v[160:163], v168 offset:3088
	ds_read_b128 v[196:199], v169 offset:3088
	v_mfma_f32_16x16x32_f16 v[84:87], v[132:135], v[242:245], v[84:87]
	v_mfma_f32_16x16x32_f16 v[88:91], v[136:139], v[242:245], v[88:91]
	v_mfma_f32_16x16x32_f16 v[92:95], v[140:143], v[242:245], v[92:95]
	v_mfma_f32_16x16x32_f16 v[96:99], v[144:147], v[242:245], v[96:99]
	v_mfma_f32_16x16x32_f16 v[100:103], v[132:135], v[246:249], v[100:103]
	v_mfma_f32_16x16x32_f16 v[104:107], v[136:139], v[246:249], v[104:107]
	v_mfma_f32_16x16x32_f16 v[108:111], v[140:143], v[246:249], v[108:111]
	v_mfma_f32_16x16x32_f16 v[112:115], v[144:147], v[246:249], v[112:115]
	v_mfma_f32_16x16x32_f16 v[116:119], v[132:135], v[250:253], v[116:119]
	v_mfma_f32_16x16x32_f16 v[120:123], v[136:139], v[250:253], v[120:123]
	v_mfma_f32_16x16x32_f16 v[124:127], v[140:143], v[250:253], v[124:127]
	v_mfma_f32_16x16x32_f16 v[128:131], v[144:147], v[250:253], v[128:131]
	s_waitcnt lgkmcnt(0)
	s_mov_b32 s47, s48
	v_add_u32_e32 v169, s47, v164
	v_mfma_f32_16x16x32_f16 v[4:7], v[148:151], v[184:187], v[4:7]
	ds_read_b128 v[238:241], v169 offset:4112
	v_mfma_f32_16x16x32_f16 v[8:11], v[152:155], v[184:187], v[8:11]
	ds_read_b128 v[242:245], v169 offset:5136
	v_mfma_f32_16x16x32_f16 v[12:15], v[156:159], v[184:187], v[12:15]
	ds_read_b128 v[246:249], v169 offset:6160
	v_mfma_f32_16x16x32_f16 v[16:19], v[160:163], v[184:187], v[16:19]
	ds_read_b128 v[250:253], v169 offset:7184
	v_mfma_f32_16x16x32_f16 v[20:23], v[148:151], v[188:191], v[20:23]
	v_mfma_f32_16x16x32_f16 v[24:27], v[152:155], v[188:191], v[24:27]
	v_mfma_f32_16x16x32_f16 v[28:31], v[156:159], v[188:191], v[28:31]
	v_mfma_f32_16x16x32_f16 v[32:35], v[160:163], v[188:191], v[32:35]
	v_mfma_f32_16x16x32_f16 v[36:39], v[148:151], v[192:195], v[36:39]
	v_mfma_f32_16x16x32_f16 v[40:43], v[152:155], v[192:195], v[40:43]
	v_mfma_f32_16x16x32_f16 v[44:47], v[156:159], v[192:195], v[44:47]
	v_mfma_f32_16x16x32_f16 v[48:51], v[160:163], v[192:195], v[48:51]
	v_mfma_f32_16x16x32_f16 v[52:55], v[148:151], v[196:199], v[52:55]
	v_mfma_f32_16x16x32_f16 v[56:59], v[152:155], v[196:199], v[56:59]
	v_mfma_f32_16x16x32_f16 v[60:63], v[156:159], v[196:199], v[60:63]
	v_mfma_f32_16x16x32_f16 v[64:67], v[160:163], v[196:199], v[64:67]
	s_waitcnt vmcnt(4) lgkmcnt(0)
	s_barrier
	s_add_i32 s48, s47, 0x8000
	s_cmp_lg_u32 s47, 0x18000
	s_cselect_b32 s48, s48, 0
	v_add_u32_e32 v168, s48, v165
	v_add_u32_e32 v169, s48, v164
	v_mfma_f32_16x16x32_f16 v[68:71], v[148:151], v[238:241], v[68:71]
	ds_read_b128 v[132:135], v168 offset:16
	ds_read_b128 v[184:187], v169 offset:16
	v_mfma_f32_16x16x32_f16 v[72:75], v[152:155], v[238:241], v[72:75]
	ds_read_b128 v[136:139], v168 offset:1040
	ds_read_b128 v[188:191], v169 offset:1040
	v_mfma_f32_16x16x32_f16 v[76:79], v[156:159], v[238:241], v[76:79]
	ds_read_b128 v[140:143], v168 offset:2064
	ds_read_b128 v[192:195], v169 offset:2064
	v_mfma_f32_16x16x32_f16 v[80:83], v[160:163], v[238:241], v[80:83]
	ds_read_b128 v[144:147], v168 offset:3088
	ds_read_b128 v[196:199], v169 offset:3088
	v_mfma_f32_16x16x32_f16 v[84:87], v[148:151], v[242:245], v[84:87]
	v_mfma_f32_16x16x32_f16 v[88:91], v[152:155], v[242:245], v[88:91]
	v_mfma_f32_16x16x32_f16 v[92:95], v[156:159], v[242:245], v[92:95]
	v_mfma_f32_16x16x32_f16 v[96:99], v[160:163], v[242:245], v[96:99]
	v_mfma_f32_16x16x32_f16 v[100:103], v[148:151], v[246:249], v[100:103]
	v_mfma_f32_16x16x32_f16 v[104:107], v[152:155], v[246:249], v[104:107]
	v_mfma_f32_16x16x32_f16 v[108:111], v[156:159], v[246:249], v[108:111]
	v_mfma_f32_16x16x32_f16 v[112:115], v[160:163], v[246:249], v[112:115]
	v_mfma_f32_16x16x32_f16 v[116:119], v[148:151], v[250:253], v[116:119]
	v_mfma_f32_16x16x32_f16 v[120:123], v[152:155], v[250:253], v[120:123]
	v_mfma_f32_16x16x32_f16 v[124:127], v[156:159], v[250:253], v[124:127]
	v_mfma_f32_16x16x32_f16 v[128:131], v[160:163], v[250:253], v[128:131]
	s_waitcnt lgkmcnt(0)
	s_mov_b32 s47, s48
	v_add_u32_e32 v169, s47, v164
	v_mfma_f32_16x16x32_f16 v[4:7], v[132:135], v[184:187], v[4:7]
	ds_read_b128 v[238:241], v169 offset:4112
	v_mfma_f32_16x16x32_f16 v[8:11], v[136:139], v[184:187], v[8:11]
	ds_read_b128 v[242:245], v169 offset:5136
	v_mfma_f32_16x16x32_f16 v[12:15], v[140:143], v[184:187], v[12:15]
	ds_read_b128 v[246:249], v169 offset:6160
	v_mfma_f32_16x16x32_f16 v[16:19], v[144:147], v[184:187], v[16:19]
	ds_read_b128 v[250:253], v169 offset:7184
	v_mfma_f32_16x16x32_f16 v[20:23], v[132:135], v[188:191], v[20:23]
	v_mfma_f32_16x16x32_f16 v[24:27], v[136:139], v[188:191], v[24:27]
	v_mfma_f32_16x16x32_f16 v[28:31], v[140:143], v[188:191], v[28:31]
	v_mfma_f32_16x16x32_f16 v[32:35], v[144:147], v[188:191], v[32:35]
	v_mfma_f32_16x16x32_f16 v[36:39], v[132:135], v[192:195], v[36:39]
	v_mfma_f32_16x16x32_f16 v[40:43], v[136:139], v[192:195], v[40:43]
	v_mfma_f32_16x16x32_f16 v[44:47], v[140:143], v[192:195], v[44:47]
	v_mfma_f32_16x16x32_f16 v[48:51], v[144:147], v[192:195], v[48:51]
	v_mfma_f32_16x16x32_f16 v[52:55], v[132:135], v[196:199], v[52:55]
	v_mfma_f32_16x16x32_f16 v[56:59], v[136:139], v[196:199], v[56:59]
	v_mfma_f32_16x16x32_f16 v[60:63], v[140:143], v[196:199], v[60:63]
	v_mfma_f32_16x16x32_f16 v[64:67], v[144:147], v[196:199], v[64:67]
	s_waitcnt vmcnt(0) lgkmcnt(0)
	s_barrier
	s_add_i32 s48, s47, 0x8000
	s_cmp_lg_u32 s47, 0x18000
	s_cselect_b32 s48, s48, 0
	v_add_u32_e32 v168, s48, v165
	v_add_u32_e32 v169, s48, v164
	v_mfma_f32_16x16x32_f16 v[68:71], v[132:135], v[238:241], v[68:71]
	ds_read_b128 v[148:151], v168 offset:16
	ds_read_b128 v[184:187], v169 offset:16
	v_mfma_f32_16x16x32_f16 v[72:75], v[136:139], v[238:241], v[72:75]
	ds_read_b128 v[152:155], v168 offset:1040
	ds_read_b128 v[188:191], v169 offset:1040
	v_mfma_f32_16x16x32_f16 v[76:79], v[140:143], v[238:241], v[76:79]
	ds_read_b128 v[156:159], v168 offset:2064
	ds_read_b128 v[192:195], v169 offset:2064
	v_mfma_f32_16x16x32_f16 v[80:83], v[144:147], v[238:241], v[80:83]
	ds_read_b128 v[160:163], v168 offset:3088
	ds_read_b128 v[196:199], v169 offset:3088
	v_mfma_f32_16x16x32_f16 v[84:87], v[132:135], v[242:245], v[84:87]
	v_mfma_f32_16x16x32_f16 v[88:91], v[136:139], v[242:245], v[88:91]
	v_mfma_f32_16x16x32_f16 v[92:95], v[140:143], v[242:245], v[92:95]
	v_mfma_f32_16x16x32_f16 v[96:99], v[144:147], v[242:245], v[96:99]
	v_mfma_f32_16x16x32_f16 v[100:103], v[132:135], v[246:249], v[100:103]
	v_mfma_f32_16x16x32_f16 v[104:107], v[136:139], v[246:249], v[104:107]
	v_mfma_f32_16x16x32_f16 v[108:111], v[140:143], v[246:249], v[108:111]
	v_mfma_f32_16x16x32_f16 v[112:115], v[144:147], v[246:249], v[112:115]
	v_mfma_f32_16x16x32_f16 v[116:119], v[132:135], v[250:253], v[116:119]
	v_mfma_f32_16x16x32_f16 v[120:123], v[136:139], v[250:253], v[120:123]
	v_mfma_f32_16x16x32_f16 v[124:127], v[140:143], v[250:253], v[124:127]
	v_mfma_f32_16x16x32_f16 v[128:131], v[144:147], v[250:253], v[128:131]
	s_waitcnt lgkmcnt(0)
	s_mov_b32 s47, s48
	v_add_u32_e32 v169, s47, v164
	v_mfma_f32_16x16x32_f16 v[4:7], v[148:151], v[184:187], v[4:7]
	ds_read_b128 v[238:241], v169 offset:4112
	v_mfma_f32_16x16x32_f16 v[8:11], v[152:155], v[184:187], v[8:11]
	ds_read_b128 v[242:245], v169 offset:5136
	v_mfma_f32_16x16x32_f16 v[12:15], v[156:159], v[184:187], v[12:15]
	ds_read_b128 v[246:249], v169 offset:6160
	v_mfma_f32_16x16x32_f16 v[16:19], v[160:163], v[184:187], v[16:19]
	ds_read_b128 v[250:253], v169 offset:7184
	v_mfma_f32_16x16x32_f16 v[20:23], v[148:151], v[188:191], v[20:23]
	v_mfma_f32_16x16x32_f16 v[24:27], v[152:155], v[188:191], v[24:27]
	v_mfma_f32_16x16x32_f16 v[28:31], v[156:159], v[188:191], v[28:31]
	v_mfma_f32_16x16x32_f16 v[32:35], v[160:163], v[188:191], v[32:35]
	v_mfma_f32_16x16x32_f16 v[36:39], v[148:151], v[192:195], v[36:39]
	v_mfma_f32_16x16x32_f16 v[40:43], v[152:155], v[192:195], v[40:43]
	v_mfma_f32_16x16x32_f16 v[44:47], v[156:159], v[192:195], v[44:47]
	v_mfma_f32_16x16x32_f16 v[48:51], v[160:163], v[192:195], v[48:51]
	v_mfma_f32_16x16x32_f16 v[52:55], v[148:151], v[196:199], v[52:55]
	v_mfma_f32_16x16x32_f16 v[56:59], v[152:155], v[196:199], v[56:59]
	v_mfma_f32_16x16x32_f16 v[60:63], v[156:159], v[196:199], v[60:63]
	v_mfma_f32_16x16x32_f16 v[64:67], v[160:163], v[196:199], v[64:67]
	s_waitcnt lgkmcnt(0)
	s_barrier
	v_mfma_f32_16x16x32_f16 v[68:71], v[148:151], v[238:241], v[68:71]
	v_mfma_f32_16x16x32_f16 v[72:75], v[152:155], v[238:241], v[72:75]
	v_mfma_f32_16x16x32_f16 v[76:79], v[156:159], v[238:241], v[76:79]
	v_mfma_f32_16x16x32_f16 v[80:83], v[160:163], v[238:241], v[80:83]
	v_mfma_f32_16x16x32_f16 v[84:87], v[148:151], v[242:245], v[84:87]
	v_mfma_f32_16x16x32_f16 v[88:91], v[152:155], v[242:245], v[88:91]
	v_mfma_f32_16x16x32_f16 v[92:95], v[156:159], v[242:245], v[92:95]
	v_mfma_f32_16x16x32_f16 v[96:99], v[160:163], v[242:245], v[96:99]
	v_mfma_f32_16x16x32_f16 v[100:103], v[148:151], v[246:249], v[100:103]
	v_mfma_f32_16x16x32_f16 v[104:107], v[152:155], v[246:249], v[104:107]
	v_mfma_f32_16x16x32_f16 v[108:111], v[156:159], v[246:249], v[108:111]
	v_mfma_f32_16x16x32_f16 v[112:115], v[160:163], v[246:249], v[112:115]
	v_mfma_f32_16x16x32_f16 v[116:119], v[148:151], v[250:253], v[116:119]
	v_mfma_f32_16x16x32_f16 v[120:123], v[152:155], v[250:253], v[120:123]
	v_mfma_f32_16x16x32_f16 v[124:127], v[156:159], v[250:253], v[124:127]
	v_mfma_f32_16x16x32_f16 v[128:131], v[160:163], v[250:253], v[128:131]
	s_mul_i32 s82, s52, 0xc00
	s_add_u32 s80, s28, s82
	s_addc_u32 s81, s29, 0
	s_lshl_b32 s82, s51, 1
	s_add_u32 s80, s80, s82
	s_addc_u32 s81, s81, 0
	v_and_b32_e32 v172, 15, v200
	v_bfe_u32 v173, v200, 4, 2
	v_bfe_u32 v174, v200, 6, 2
	v_bfe_u32 v175, v200, 8, 1
	v_lshl_or_b32 v175, v175, 7, v172
	v_mul_u32_u24_e32 v175, 0xc00, v175
	v_lshlrev_b32_e32 v174, 6, v174
	v_lshl_or_b32 v174, v173, 2, v174
	v_lshl_add_u32 v177, v174, 1, v175
	v_cvt_pk_f16_f32 v172, v4, v5
	v_cvt_pk_f16_f32 v173, v6, v7
	global_store_dwordx2 v177, v[172:173], s[80:81]
	v_cvt_pk_f16_f32 v174, v8, v9
	v_cvt_pk_f16_f32 v175, v10, v11
	global_store_dwordx2 v177, v[174:175], s[80:81] offset:32
	v_cvt_pk_f16_f32 v172, v12, v13
	v_cvt_pk_f16_f32 v173, v14, v15
	global_store_dwordx2 v177, v[172:173], s[80:81] offset:64
	v_cvt_pk_f16_f32 v174, v16, v17
	v_cvt_pk_f16_f32 v175, v18, v19
	global_store_dwordx2 v177, v[174:175], s[80:81] offset:96
	v_add_u32_e32 v177, 0xc000, v177
	v_cvt_pk_f16_f32 v172, v20, v21
	v_cvt_pk_f16_f32 v173, v22, v23
	global_store_dwordx2 v177, v[172:173], s[80:81]
	v_cvt_pk_f16_f32 v174, v24, v25
	v_cvt_pk_f16_f32 v175, v26, v27
	global_store_dwordx2 v177, v[174:175], s[80:81] offset:32
	v_cvt_pk_f16_f32 v172, v28, v29
	v_cvt_pk_f16_f32 v173, v30, v31
	global_store_dwordx2 v177, v[172:173], s[80:81] offset:64
	v_cvt_pk_f16_f32 v174, v32, v33
	v_cvt_pk_f16_f32 v175, v34, v35
	global_store_dwordx2 v177, v[174:175], s[80:81] offset:96
	v_add_u32_e32 v177, 0xc000, v177
	v_cvt_pk_f16_f32 v172, v36, v37
	v_cvt_pk_f16_f32 v173, v38, v39
	global_store_dwordx2 v177, v[172:173], s[80:81]
	v_cvt_pk_f16_f32 v174, v40, v41
	v_cvt_pk_f16_f32 v175, v42, v43
	global_store_dwordx2 v177, v[174:175], s[80:81] offset:32
	v_cvt_pk_f16_f32 v172, v44, v45
	v_cvt_pk_f16_f32 v173, v46, v47
	global_store_dwordx2 v177, v[172:173], s[80:81] offset:64
	v_cvt_pk_f16_f32 v174, v48, v49
	v_cvt_pk_f16_f32 v175, v50, v51
	global_store_dwordx2 v177, v[174:175], s[80:81] offset:96
	v_add_u32_e32 v177, 0xc000, v177
	v_cvt_pk_f16_f32 v172, v52, v53
	v_cvt_pk_f16_f32 v173, v54, v55
	global_store_dwordx2 v177, v[172:173], s[80:81]
	v_cvt_pk_f16_f32 v174, v56, v57
	v_cvt_pk_f16_f32 v175, v58, v59
	global_store_dwordx2 v177, v[174:175], s[80:81] offset:32
	v_cvt_pk_f16_f32 v172, v60, v61
	v_cvt_pk_f16_f32 v173, v62, v63
	global_store_dwordx2 v177, v[172:173], s[80:81] offset:64
	v_cvt_pk_f16_f32 v174, v64, v65
	v_cvt_pk_f16_f32 v175, v66, v67
	global_store_dwordx2 v177, v[174:175], s[80:81] offset:96
	v_add_u32_e32 v177, 0xc000, v177
	v_cvt_pk_f16_f32 v172, v68, v69
	v_cvt_pk_f16_f32 v173, v70, v71
	global_store_dwordx2 v177, v[172:173], s[80:81]
	v_cvt_pk_f16_f32 v174, v72, v73
	v_cvt_pk_f16_f32 v175, v74, v75
	global_store_dwordx2 v177, v[174:175], s[80:81] offset:32
	v_cvt_pk_f16_f32 v172, v76, v77
	v_cvt_pk_f16_f32 v173, v78, v79
	global_store_dwordx2 v177, v[172:173], s[80:81] offset:64
	v_cvt_pk_f16_f32 v174, v80, v81
	v_cvt_pk_f16_f32 v175, v82, v83
	global_store_dwordx2 v177, v[174:175], s[80:81] offset:96
	v_add_u32_e32 v177, 0xc000, v177
	v_cvt_pk_f16_f32 v172, v84, v85
	v_cvt_pk_f16_f32 v173, v86, v87
	global_store_dwordx2 v177, v[172:173], s[80:81]
	v_cvt_pk_f16_f32 v174, v88, v89
	v_cvt_pk_f16_f32 v175, v90, v91
	global_store_dwordx2 v177, v[174:175], s[80:81] offset:32
	v_cvt_pk_f16_f32 v172, v92, v93
	v_cvt_pk_f16_f32 v173, v94, v95
	global_store_dwordx2 v177, v[172:173], s[80:81] offset:64
	v_cvt_pk_f16_f32 v174, v96, v97
	v_cvt_pk_f16_f32 v175, v98, v99
	global_store_dwordx2 v177, v[174:175], s[80:81] offset:96
	v_add_u32_e32 v177, 0xc000, v177
	v_cvt_pk_f16_f32 v172, v100, v101
	v_cvt_pk_f16_f32 v173, v102, v103
	global_store_dwordx2 v177, v[172:173], s[80:81]
	v_cvt_pk_f16_f32 v174, v104, v105
	v_cvt_pk_f16_f32 v175, v106, v107
	global_store_dwordx2 v177, v[174:175], s[80:81] offset:32
	v_cvt_pk_f16_f32 v172, v108, v109
	v_cvt_pk_f16_f32 v173, v110, v111
	global_store_dwordx2 v177, v[172:173], s[80:81] offset:64
	v_cvt_pk_f16_f32 v174, v112, v113
	v_cvt_pk_f16_f32 v175, v114, v115
	global_store_dwordx2 v177, v[174:175], s[80:81] offset:96
	v_add_u32_e32 v177, 0xc000, v177
	v_cvt_pk_f16_f32 v172, v116, v117
	v_cvt_pk_f16_f32 v173, v118, v119
	global_store_dwordx2 v177, v[172:173], s[80:81]
	v_cvt_pk_f16_f32 v174, v120, v121
	v_cvt_pk_f16_f32 v175, v122, v123
	global_store_dwordx2 v177, v[174:175], s[80:81] offset:32
	v_cvt_pk_f16_f32 v172, v124, v125
	v_cvt_pk_f16_f32 v173, v126, v127
	global_store_dwordx2 v177, v[172:173], s[80:81] offset:64
	v_cvt_pk_f16_f32 v174, v128, v129
	v_cvt_pk_f16_f32 v175, v130, v131
	global_store_dwordx2 v177, v[174:175], s[80:81] offset:96
	s_nop 1
	s_add_i32 s46, s46, s76
	s_cmp_ge_i32 s46, s59
	s_cbranch_scc1 .LBB0_1133
	s_branch .LBB0_1121
